# v77 plus the dt=3 K2 transposed-fragment reads issued right after the last Q MFMA (into the freed Q it3 registers)
# baseline (speedup 1.0000x reference)
; #define LAS __attribute__((address_space(3)))
; #define LBAR() do { asm volatile("s_waitcnt lgkmcnt(0)" ::: "memory"); __builtin_amdgcn_s_barrier(); asm volatile("" ::: "memory"); } while (0)
; __device__ __forceinline__ void retention_unit(LAS unsigned char* lds, const Ptrs& P, int b, int h, int tid) {
;     ...
;         if (n < 32) {
; #pragma unroll
;             for (int j2 = 0; j2 < 2; ++j2) {
;                 const int jt = (w & 1) * 2 + j2; f32x4 a4 = (f32x4){0.f, 0.f, 0.f, 0.f};
; #pragma unroll
;                 for (int ks = 0; ks < 2; ++ks) {
;                     const bf16x8 qf = *(const LAS bf16x8*)(Qs + (16 * it3 + fr) * S72 + 32 * ks + 8 * fq), kf = *(const LAS bf16x8*)(Ks + (16 * jt + fr) * S72 + 32 * ks + 8 * fq);
;                     a4 = mfma16(kf, qf, a4); }
;                 a4 = a4 * decv[j2];
;                 v2u pw; pw.x = pk2(a4[0], a4[1]); pw.y = pk2(a4[2], a4[3]);
;                 *(LAS v2u*)(Ss + (16 * it3 + fr) * S72 + 16 * jt + 4 * fq) = pw;
;             }
;         }
;         LBAR();
;         if (n >= 1) {
; #pragma unroll
;             for (int it = 0; it < 4; ++it) { const int i = 16 * it + fr; const float mean = stat[i * 2], rstd = stat[i * 2 + 1]; const v2u sg = sgr[it];
;                 const f32x4 y = (op[it] - mean) * rstd * gng4 * (f32x4){bflo(sg.x), bfhi(sg.x), bflo(sg.y), bfhi(sg.y)};
;                 v2u pw; pw.x = pk2(y[0], y[1]); pw.y = pk2(y[2], y[3]);
;                 *(v2u*)(gol + ((size_t)(n - 1) * 64 + 16 * it) * 1024) = pw; }
;         }
;         if (n < 32) {
;             f32x4 o[4]; bf16x8 bst[2], bv[2];
; #pragma unroll
;             for (int ks = 0; ks < 2; ++ks) { bst[ks] = *(const LAS bf16x8*)(St + (16 * w + fr) * S72 + 32 * ks + 8 * fq); bv[ks] = tr_frag(bufc + ROFF_V, S144 * 2, w, ks, fq, fr); }
; #pragma unroll
;             for (int it = 0; it < 4; ++it) { o[it] = (f32x4){0.f, 0.f, 0.f, 0.f};
; #pragma unroll
;                 for (int ks = 0; ks < 2; ++ks) { const bf16x8 qf = *(const LAS bf16x8*)(Qs + (16 * it + fr) * S72 + 32 * ks + 8 * fq); o[it] = mfma16(bst[ks], qf, o[it]); }
;                 o[it] = o[it] * dqv[it];
; #pragma unroll
;                 for (int ks = 0; ks < 2; ++ks) { const bf16x8 sf = *(const LAS bf16x8*)(Ss + (16 * it + fr) * S72 + 32 * ks + 8 * fq); o[it] = mfma16(bv[ks], sf, o[it]); }
;             }
.LBB0_657:
	s_or_b64 exec, exec, s[18:19]
	v_lshl_add_u32 v60, v155, 1, s90
	v_add_u32_e32 v61, v60, v179
	s_waitcnt lgkmcnt(0)
	ds_read_b128 v[56:59], v61 offset:9216
	v_add_u32_e32 v75, v60, v62
	ds_read_b128 v[184:187], v61 offset:9280
	ds_read_b128 v[188:191], v75
	ds_read_b128 v[192:195], v75 offset:64
	v_add_u32_e32 v60, v60, v178
	s_waitcnt vmcnt(7)
	v_and_b32_e32 v61, 0xffff0000, v54
	v_add_u32_e32 v75, 0, v160
	v_add_u32_e32 v143, 0x21400, v75
	v_lshl_add_u64 v[120:121], s[26:27], 0, v[114:115]
	v_add3_u32 v204, s90, v82, v169
	s_waitcnt lgkmcnt(1)
	v_mfma_f32_16x16x32_bf16 v[56:59], v[56:59], v[188:191], 0
	s_add_i32 s18, s90, s87
	s_waitcnt vmcnt(5)
	v_lshlrev_b32_e32 v200, 16, v122
	v_and_b32_e32 v201, 0xffff0000, v122
	s_waitcnt lgkmcnt(0)
	v_mfma_f32_16x16x32_bf16 v[56:59], v[184:187], v[192:195], v[56:59]
	v_lshlrev_b32_e32 v122, 16, v123
	v_and_b32_e32 v123, 0xffff0000, v123
	v_add3_u32 v212, s90, v162, v170
	v_mov_b32_e32 v75, v74
	v_pk_mul_f32 v[18:19], v[74:75], v[18:19]
	s_nop 2
	v_pk_mul_f32 v[58:59], v[100:101], v[58:59]
	v_pk_mul_f32 v[56:57], v[98:99], v[56:57]
	v_pk_mul_f32 v[16:17], v[76:77], v[16:17]
	v_cvt_pk_bf16_f32 v56, v56, v57
	v_cvt_pk_bf16_f32 v57, v58, v59
	ds_write_b64 v177, v[56:57]
	ds_read_b128 v[56:59], v60 offset:9216
	ds_read_b128 v[184:187], v60 offset:9280
	ds_read_b128 v[216:219], v204
	ds_read_b128 v[220:223], v204 offset:64
	ds_read_b128 v[224:227], v204 offset:2304
	ds_read_b128 v[228:231], v204 offset:2368
	ds_read_b128 v[232:235], v204 offset:4608
	ds_read_b128 v[236:239], v204 offset:4672
	ds_read_b128 v[240:243], v204 offset:6912
	ds_read_b128 v[244:247], v204 offset:6976
	s_waitcnt lgkmcnt(9)
	v_mfma_f32_16x16x32_bf16 v[56:59], v[56:59], v[188:191], 0
	v_lshlrev_b32_e32 v60, 16, v54
	v_lshlrev_b32_e32 v188, 16, v55
	v_and_b32_e32 v189, 0xffff0000, v55
	s_waitcnt lgkmcnt(8)
	v_mfma_f32_16x16x32_bf16 v[54:57], v[184:187], v[192:195], v[56:59]
	v_mul_f32_e64 v14, v74, v14
	v_mul_f32_e64 v15, v75, v15
	v_pk_mul_f32 v[12:13], v[76:77], v[12:13]
	v_pk_mul_f32 v[10:11], v[74:75], v[10:11]
	v_add_co_u32_e32 v58, vcc, s66, v120
	v_pk_mul_f32 v[8:9], v[76:77], v[8:9]
	s_nop 1
	v_pk_mul_f32 v[56:57], v[94:95], v[56:57]
	v_pk_mul_f32 v[54:55], v[92:93], v[54:55]
	v_addc_co_u32_e32 v59, vcc, 0, v121, vcc
	v_cvt_pk_bf16_f32 v54, v54, v55
	v_cvt_pk_bf16_f32 v55, v56, v57
	ds_write_b64 v142, v[54:55]
	s_waitcnt lgkmcnt(0)
	s_barrier
	ds_read2_b64 v[54:57], v143 offset1:16
	ds_read_b128 v[184:187], v137
	v_pk_mul_f32 v[6:7], v[74:75], v[6:7]
	v_pk_mul_f32 v[4:5], v[76:77], v[4:5]
	v_lshl_add_u64 v[110:111], v[110:111], 0, s[8:9]
	s_waitcnt lgkmcnt(1)
	v_sub_f32_e32 v41, v41, v54
	v_sub_f32_e32 v40, v40, v54
	v_sub_f32_e32 v43, v43, v54
	v_sub_f32_e32 v42, v42, v54
	v_pk_mul_f32 v[42:43], v[54:55], v[42:43] op_sel:[1,0]
	v_pk_mul_f32 v[40:41], v[54:55], v[40:41] op_sel:[1,0]
	v_pk_mul_f32 v[42:43], v[2:3], v[42:43]
	v_pk_mul_f32 v[40:41], v[0:1], v[40:41]
	v_pk_mul_f32 v[42:43], v[42:43], v[188:189]
	v_pk_mul_f32 v[40:41], v[40:41], v[60:61]
	v_sub_f32_e32 v45, v45, v56
	v_cvt_pk_bf16_f32 v40, v40, v41
	v_cvt_pk_bf16_f32 v41, v42, v43
	v_sub_f32_e32 v44, v44, v56
	global_store_dwordx2 v[58:59], v[40:41], off
	v_sub_f32_e32 v41, v47, v56
	v_sub_f32_e32 v40, v46, v56
	v_pk_mul_f32 v[40:41], v[56:57], v[40:41] op_sel:[1,0]
	v_pk_mul_f32 v[42:43], v[56:57], v[44:45] op_sel:[1,0]
	ds_read2_b64 v[54:57], v143 offset0:32 offset1:48
	v_pk_mul_f32 v[42:43], v[0:1], v[42:43]
	v_pk_mul_f32 v[40:41], v[2:3], v[40:41]
	v_lshlrev_b32_e32 v44, 16, v52
	v_and_b32_e32 v45, 0xffff0000, v52
	v_lshlrev_b32_e32 v46, 16, v53
	v_and_b32_e32 v47, 0xffff0000, v53
	v_pk_mul_f32 v[40:41], v[40:41], v[46:47]
	v_pk_mul_f32 v[42:43], v[42:43], v[44:45]
	ds_read_b128 v[188:191], v137 offset:64
	v_cvt_pk_bf16_f32 v42, v42, v43
	v_cvt_pk_bf16_f32 v43, v40, v41
	v_add_co_u32_e32 v40, vcc, s67, v120
	s_nop 0
	v_addc_co_u32_e32 v41, vcc, 0, v121, vcc
	global_store_dwordx2 v[40:41], v[42:43], off
	s_waitcnt lgkmcnt(1)
	v_sub_f32_e32 v41, v49, v54
	v_sub_f32_e32 v40, v48, v54
	v_sub_f32_e32 v43, v51, v54
	v_sub_f32_e32 v42, v50, v54
	v_pk_mul_f32 v[40:41], v[54:55], v[40:41] op_sel:[1,0]
	v_pk_mul_f32 v[192:193], v[54:55], v[42:43] op_sel:[1,0]
	v_pk_mul_f32 v[196:197], v[0:1], v[40:41]
	s_waitcnt lgkmcnt(0)
	v_mfma_f32_16x16x32_bf16 v[40:43], v[184:187], v[216:219], 0
	v_add3_u32 v48, s18, v162, v168
	ds_read_b64_tr_b16 v[58:59], v48 offset:27648
	ds_read_b64_tr_b16 v[60:61], v48 offset:28800
	ds_read_b64_tr_b16 v[52:53], v48 offset:36864
	ds_read_b64_tr_b16 v[54:55], v48 offset:38016
	ds_read_b128 v[48:51], v129
	v_pk_mul_f32 v[192:193], v[2:3], v[192:193]
	v_mfma_f32_16x16x32_bf16 v[40:43], v[188:191], v[220:223], v[40:43]
	ds_read_b128 v[44:47], v129 offset:64
	v_pk_mul_f32 v[122:123], v[192:193], v[122:123]
	ds_read_b128 v[192:195], v129 offset:2304
	v_lshl_add_u64 v[112:113], v[112:113], 0, s[12:13]
	v_lshl_add_u64 v[114:115], v[114:115], 0, s[14:15]
	s_nop 2
	v_pk_mul_f32 v[42:43], v[108:109], v[42:43]
	v_pk_mul_f32 v[40:41], v[90:91], v[40:41]
	s_cmp_lg_u32 s89, 30
	v_lshl_add_u64 v[116:117], v[116:117], 0, s[12:13]
	s_waitcnt lgkmcnt(2)
	v_mfma_f32_16x16x32_bf16 v[40:43], v[58:61], v[48:51], v[40:43]
	s_waitcnt lgkmcnt(1)
	v_mfma_f32_16x16x32_bf16 v[40:43], v[52:55], v[44:47], v[40:43]
	s_waitcnt lgkmcnt(0)
	v_mfma_f32_16x16x32_bf16 v[48:51], v[184:187], v[224:227], 0
	s_waitcnt lgkmcnt(0)
; #define LAS __attribute__((address_space(3)))
; __device__ __forceinline__ unsigned pk2(float lo, float hi) { return pg8::cvt_pk_bf16(lo, hi); }
; __device__ __forceinline__ f32x4 mfma16(bf16x8 a, bf16x8 b, f32x4 c) { return __builtin_amdgcn_mfma_f32_16x16x32_bf16(a, b, c, 0, 0, 0); }
; __device__ __forceinline__ void retention_unit(LAS unsigned char* lds, const Ptrs& P, int b, int h, int tid) {
;     ...
;         if (n < 32) {
;             f32x4 o[4]; bf16x8 bst[2], bv[2];
; #pragma unroll
;             for (int ks = 0; ks < 2; ++ks) { bst[ks] = *(const LAS bf16x8*)(St + (16 * w + fr) * S72 + 32 * ks + 8 * fq); bv[ks] = tr_frag(bufc + ROFF_V, S144 * 2, w, ks, fq, fr); }
; #pragma unroll
;             for (int it = 0; it < 4; ++it) { o[it] = (f32x4){0.f, 0.f, 0.f, 0.f};
; #pragma unroll
;                 for (int ks = 0; ks < 2; ++ks) { const bf16x8 qf = *(const LAS bf16x8*)(Qs + (16 * it + fr) * S72 + 32 * ks + 8 * fq); o[it] = mfma16(bst[ks], qf, o[it]); }
;                 o[it] = o[it] * dqv[it];
; #pragma unroll
;                 for (int ks = 0; ks < 2; ++ks) { const bf16x8 sf = *(const LAS bf16x8*)(Ss + (16 * it + fr) * S72 + 32 * ks + 8 * fq); o[it] = mfma16(bv[ks], sf, o[it]); }
;             }
; #pragma unroll
;             for (int dt = 0; dt < 4; ++dt) { st[dt] = st[dt] * dch;
; #pragma unroll
;                 for (int ks = 0; ks < 2; ++ks) { const bf16x8 kf = tr_frag(bufc + ROFF_K2, S72 * 2, dt, ks, fq, fr); st[dt] = mfma16(kf, bv[ks], st[dt]); }
;                 v2u pw; pw.x = pk2(st[dt][0], st[dt][1]); pw.y = pk2(st[dt][2], st[dt][3]);
;                 *(LAS v2u*)(St + (16 * w + fr) * S72 + 16 * dt + 4 * fq) = pw; }
; #pragma unroll
;             for (int it = 0; it < 4; ++it) { const f32x4 v = o[it]; typedef float f32x2 __attribute__((ext_vector_type(2)));
;                 *(LAS f32x2*)(part + ((16 * it + fr) * 32 + w * 4 + fq) * 2) = (f32x2){(v[0] + v[1]) + (v[2] + v[3]), (v[0] * v[0] + v[1] * v[1]) + (v[2] * v[2] + v[3] * v[3])};
;                 op[it] = v; }
	v_mfma_f32_16x16x32_bf16 v[44:47], v[188:191], v[228:231], v[48:51]
	ds_read_b64_tr_b16 v[216:217], v212 offset:18432
	ds_read_b64_tr_b16 v[218:219], v212 offset:19008
	ds_read_b64_tr_b16 v[220:221], v212 offset:23040
	ds_read_b64_tr_b16 v[222:223], v212 offset:23616
	ds_read_b64_tr_b16 v[224:225], v212 offset:18464
	ds_read_b64_tr_b16 v[226:227], v212 offset:19040
	ds_read_b64_tr_b16 v[228:229], v212 offset:23072
	ds_read_b64_tr_b16 v[230:231], v212 offset:23648
	s_nop 5
	ds_read_b128 v[48:51], v129 offset:2368
	s_nop 0
	v_pk_mul_f32 v[46:47], v[106:107], v[46:47]
	v_pk_mul_f32 v[44:45], v[78:79], v[44:45]
	s_nop 1
	v_mfma_f32_16x16x32_bf16 v[44:47], v[58:61], v[192:195], v[44:47]
	v_mul_f32_e64 v192, v196, v200
	v_mul_f32_e64 v193, v197, v201
	ds_read_b128 v[200:203], v129 offset:4608
	v_cvt_pk_bf16_f32 v192, v192, v193
	s_waitcnt lgkmcnt(1)
	v_mfma_f32_16x16x32_bf16 v[44:47], v[52:55], v[48:51], v[44:47]
	v_cvt_pk_bf16_f32 v193, v122, v123
	v_add_co_u32_e32 v122, vcc, s68, v120
	v_sub_f32_e32 v197, v23, v56
	s_nop 0
	v_addc_co_u32_e32 v123, vcc, 0, v121, vcc
	global_store_dwordx2 v[122:123], v[192:193], off
	s_waitcnt lgkmcnt(0)
	v_mfma_f32_16x16x32_bf16 v[48:51], v[184:187], v[232:235], 0
	v_sub_f32_e32 v123, v21, v56
	v_sub_f32_e32 v122, v20, v56
	v_sub_f32_e32 v196, v22, v56
	s_waitcnt lgkmcnt(0)
	v_mfma_f32_16x16x32_bf16 v[48:51], v[188:191], v[236:239], v[48:51]
	ds_read_b64_tr_b16 v[232:233], v212 offset:18496
	ds_read_b64_tr_b16 v[234:235], v212 offset:19072
	ds_read_b64_tr_b16 v[236:237], v212 offset:23104
	ds_read_b64_tr_b16 v[238:239], v212 offset:23680
	ds_read_b128 v[192:195], v129 offset:4672
	v_pk_mul_f32 v[196:197], v[56:57], v[196:197] op_sel:[1,0]
	v_pk_mul_f32 v[56:57], v[56:57], v[122:123] op_sel:[1,0]
	v_pk_mul_f32 v[122:123], v[2:3], v[196:197]
	v_pk_mul_f32 v[56:57], v[0:1], v[56:57]
	s_nop 2
	v_pk_mul_f32 v[50:51], v[104:105], v[50:51]
	v_pk_mul_f32 v[48:49], v[86:87], v[48:49]
	s_waitcnt vmcnt(7)
	v_lshlrev_b32_e32 v196, 16, v118
	v_and_b32_e32 v197, 0xffff0000, v118
	v_mfma_f32_16x16x32_bf16 v[48:51], v[58:61], v[200:203], v[48:51]
	s_waitcnt lgkmcnt(0)
	v_mfma_f32_16x16x32_bf16 v[16:19], v[216:219], v[58:61], v[16:19]
	s_waitcnt lgkmcnt(0)
	v_mfma_f32_16x16x32_bf16 v[16:19], v[220:223], v[52:55], v[16:19]
	v_mfma_f32_16x16x32_bf16 v[48:51], v[52:55], v[192:195], v[48:51]
	ds_read_b128 v[204:207], v129 offset:6912
	ds_read_b128 v[208:211], v129 offset:6976
	s_nop 2
	v_cvt_pk_bf16_f32 v20, v16, v17
	v_cvt_pk_bf16_f32 v21, v18, v19
	ds_write_b64 v132, v[20:21]
	s_waitcnt lgkmcnt(3)
	v_mfma_f32_16x16x32_bf16 v[184:187], v[184:187], v[240:243], 0
	s_waitcnt lgkmcnt(0)
	v_mfma_f32_16x16x32_bf16 v[12:15], v[224:227], v[58:61], v[12:15]
	s_waitcnt lgkmcnt(0)
	v_mfma_f32_16x16x32_bf16 v[12:15], v[228:231], v[52:55], v[12:15]
	v_mfma_f32_16x16x32_bf16 v[184:187], v[188:191], v[244:247], v[184:187]
	ds_read_b64_tr_b16 v[240:241], v212 offset:18528
	ds_read_b64_tr_b16 v[242:243], v212 offset:19104
	ds_read_b64_tr_b16 v[244:245], v212 offset:23136
	ds_read_b64_tr_b16 v[246:247], v212 offset:23712
	s_nop 6
	v_cvt_pk_bf16_f32 v20, v12, v13
	v_cvt_pk_bf16_f32 v21, v14, v15
	ds_write_b64 v132, v[20:21] offset:32
	s_waitcnt lgkmcnt(0)
	v_mfma_f32_16x16x32_bf16 v[8:11], v[232:235], v[58:61], v[8:11]
	v_mul_f32_e64 v186, v96, v186
	v_mul_f32_e64 v187, v97, v187
	v_pk_mul_f32 v[184:185], v[88:89], v[184:185]
	v_lshlrev_b32_e32 v20, 16, v119
	s_waitcnt lgkmcnt(0)
	v_mfma_f32_16x16x32_bf16 v[8:11], v[236:239], v[52:55], v[8:11]
	v_and_b32_e32 v21, 0xffff0000, v119
	v_pk_mul_f32 v[20:21], v[122:123], v[20:21]
	v_mfma_f32_16x16x32_bf16 v[184:187], v[58:61], v[204:207], v[184:187]
	s_nop 4
	v_cvt_pk_bf16_f32 v22, v8, v9
	v_cvt_pk_bf16_f32 v23, v10, v11
	ds_write_b64 v132, v[22:23] offset:64
	v_pk_mul_f32 v[22:23], v[56:57], v[196:197]
	v_cvt_pk_bf16_f32 v57, v20, v21
	v_cvt_pk_bf16_f32 v56, v22, v23
	v_mfma_f32_16x16x32_bf16 v[20:23], v[52:55], v[208:211], v[184:187]
	s_nop 2
	s_waitcnt lgkmcnt(0)
	v_mfma_f32_16x16x32_bf16 v[4:7], v[240:243], v[58:61], v[4:7]
	v_add_co_u32_e32 v58, vcc, s69, v120
	s_waitcnt lgkmcnt(0)
	v_mfma_f32_16x16x32_bf16 v[4:7], v[244:247], v[52:55], v[4:7]
	v_addc_co_u32_e32 v59, vcc, 0, v121, vcc
	global_store_dwordx2 v[58:59], v[56:57], off
	v_mul_f32_e32 v55, v41, v41
	v_mul_f32_e32 v57, v42, v42
	s_nop 3
	v_cvt_pk_bf16_f32 v52, v4, v5
	v_cvt_pk_bf16_f32 v53, v6, v7
	ds_write_b64 v132, v[52:53] offset:96
	v_mul_f32_e32 v53, v40, v40
	v_mul_f32_e32 v59, v43, v43
	v_mov_b32_e32 v52, v40
	v_mov_b32_e32 v54, v41
	v_mov_b32_e32 v56, v42
	v_mov_b32_e32 v58, v43
	v_pk_add_f32 v[52:53], v[52:53], v[54:55]
	v_pk_add_f32 v[54:55], v[56:57], v[58:59]
	v_mul_f32_e32 v57, v46, v46
	v_pk_add_f32 v[52:53], v[52:53], v[54:55]
	ds_write_b64 v133, v[52:53]
	v_mul_f32_e32 v53, v44, v44
	v_mul_f32_e32 v55, v45, v45
	v_mul_f32_e32 v59, v47, v47
	v_mov_b32_e32 v52, v44
	v_mov_b32_e32 v54, v45
	v_mov_b32_e32 v56, v46
	v_mov_b32_e32 v58, v47
	v_pk_add_f32 v[52:53], v[52:53], v[54:55]
	v_pk_add_f32 v[54:55], v[56:57], v[58:59]
	v_mul_f32_e32 v57, v50, v50
	v_pk_add_f32 v[52:53], v[52:53], v[54:55]
	ds_write_b64 v134, v[52:53]
	v_mul_f32_e32 v53, v48, v48
	v_mul_f32_e32 v55, v49, v49
	v_mul_f32_e32 v59, v51, v51
	v_mov_b32_e32 v52, v48
	v_mov_b32_e32 v54, v49
	v_mov_b32_e32 v56, v50
	v_mov_b32_e32 v58, v51
	v_pk_add_f32 v[52:53], v[52:53], v[54:55]
	v_pk_add_f32 v[54:55], v[56:57], v[58:59]
	v_mul_f32_e32 v57, v22, v22
	v_pk_add_f32 v[52:53], v[52:53], v[54:55]
	ds_write_b64 v135, v[52:53]
	v_mul_f32_e32 v53, v20, v20
	v_mul_f32_e32 v55, v21, v21
	v_mul_f32_e32 v59, v23, v23
	v_mov_b32_e32 v52, v20
	v_mov_b32_e32 v54, v21
	v_mov_b32_e32 v56, v22
	v_mov_b32_e32 v58, v23
	v_pk_add_f32 v[52:53], v[52:53], v[54:55]
	v_pk_add_f32 v[54:55], v[56:57], v[58:59]
	s_nop 0
	v_pk_add_f32 v[52:53], v[52:53], v[54:55]
	ds_write_b64 v136, v[52:53]
	s_cbranch_scc0 .LBB0_660
